# in-projection RoPE epilogue: rowss loads hoisted; plain path second-half rowss load hoisted
# baseline (speedup 1.0000x reference)
;     __device__ __forceinline__ void operator()(const f32x4 (&acc)[2][2][4][2], const Unit& u, int wr, int wc, int fr, int fq) const {
;     ...
;             const bool isq = (pn == 6) || (wc < 2);
;             const int hcol = (pn == 6) ? 64 * wc : (wc < 2 ? 64 * (4 + wc) : 64 * (wc - 2));
;             bf16_t* base = qkv + (isq ? OFF_QC : OFF_KC) + hcol + 8 * fqo;
;             const int pitch = isq ? 384 : 128;
;             const float* gw = (isq ? gq : gk) + 4 * fqo;
;             const float osc = isq ? 0.125f * 1.4426950408889634f : 1.0f;
; #pragma unroll
;             for (int ai = 0; ai < 2; ++ai)
; #pragma unroll
;                 for (int m = 0; m < 4; ++m) {
;                     const int row = row0 + ai * HALF + m * 16; const int t = row & 16383;
;                     const float rv = rsqrtf(rowss[row] * (1.0f / 1024.0f) + 1e-6f);
;                     float ss = 0.f; f32x4 hv[2][2];
; #pragma unroll
;                     for (int bj = 0; bj < 2; ++bj)
; #pragma unroll
;                         for (int n = 0; n < 2; ++n) { const f32x4 v = acc[ai][bj][m][n] * rv + *(const f32x4*)(bp + bj * HALF + 4 * n); hv[bj][n] = v; ss += (v[0] * v[0] + v[1] * v[1]) + (v[2] * v[2] + v[3] * v[3]); }
;                     ss += __shfl_xor(ss, 16); ss += __shfl_xor(ss, 32);
;                     const float rinv = rsqrtf(ss * (1.0f / 64.0f) + 1e-6f) * osc;
.LBB0_259:
	s_ashr_i32 s0, s6, 6
	s_lshl_b32 s4, s6, 8
	s_ashr_i32 s1, s0, 31
	s_add_i32 s4, s4, s11
	s_lshl_b64 s[0:1], s[0:1], 13
	s_add_u32 s5, s79, s0
	s_addc_u32 s6, s10, s1
	s_lshl_b32 s0, s66, 8
	s_ashr_i32 s1, s0, 31
	s_lshl_b64 s[0:1], s[0:1], 2
	s_add_u32 s0, s5, s0
	v_mov_b32_e32 v244, v238
	s_addc_u32 s1, s6, s1
	s_add_u32 s0, s0, s80
	v_lshlrev_b32_e32 v164, 3, v244
	v_or_b32_e32 v162, s4, v237
	s_addc_u32 s1, s1, 0
	v_ashrrev_i32_e32 v165, 31, v164
	v_lshl_add_u64 v[166:167], v[164:165], 2, s[0:1]
	s_mov_b64 s[0:1], -1
	s_cmp_gt_i32 s66, 5
	v_ashrrev_i32_e32 v163, 31, v162
	v_or_b32_e32 v243, 16, v162
	v_or_b32_e32 v242, 32, v162
	v_or_b32_e32 v241, 48, v162
	s_cbranch_scc0 .LBB0_261
	s_cmp_eq_u32 s66, 6
	s_cselect_b64 s[0:1], -1, 0
	s_and_b64 s[6:7], s[0:1], exec
	v_readlane_b32 s5, v255, 23
	s_cselect_b32 s34, s81, s5
	s_or_b64 vcc, s[0:1], s[38:39]
	s_and_b64 s[0:1], vcc, exec
	s_mov_b32 s0, 0x5800000
	s_cselect_b32 s0, s0, 0x7000000
	s_add_u32 s5, s2, s0
	s_addc_u32 s6, s3, 0
	s_lshl_b64 s[0:1], s[34:35], 1
	s_add_u32 s0, s5, s0
	s_addc_u32 s1, s6, s1
	v_readlane_b32 s48, v252, 2
	v_lshl_add_u64 v[170:171], v[164:165], 1, s[0:1]
	s_and_b64 s[0:1], vcc, exec
	v_readlane_b32 s50, v252, 4
	v_readlane_b32 s52, v252, 6
	v_lshlrev_b32_e32 v130, 2, v244
	v_readlane_b32 s51, v252, 5
	v_readlane_b32 s53, v252, 7
	s_cselect_b32 s0, s50, s52
	v_ashrrev_i32_e32 v131, 31, v130
	s_cselect_b32 s1, s51, s53
	s_add_u32 s0, s0, s76
	v_lshlrev_b64 v[186:187], 2, v[130:131]
	v_and_b32_e32 v131, 64, v230
	s_addc_u32 s1, s1, s77
	v_xor_b32_e32 v130, 16, v230
	v_add_u32_e32 v131, 64, v131
	v_lshl_add_u64 v[168:169], s[0:1], 0, v[186:187]
	v_cmp_lt_i32_e64 s[0:1], v130, v131
	v_lshl_add_u64 v[172:173], v[162:163], 2, s[12:13]
	v_cndmask_b32_e32 v245, 1.0, v231, vcc
	v_cndmask_b32_e64 v130, v230, v130, s[0:1]
	v_lshlrev_b32_e32 v246, 2, v130
	v_xor_b32_e32 v130, 32, v230
	v_cmp_lt_i32_e64 s[0:1], v130, v131
	v_mov_b32_e32 v159, v129
	v_mov_b32_e32 v161, v129
	v_cndmask_b32_e64 v130, v230, v130, s[0:1]
	v_lshlrev_b32_e32 v247, 2, v130
	global_load_dword v130, v[172:173], off
	global_load_dword v248, v[172:173], off offset:64
	global_load_dword v249, v[172:173], off offset:128
	global_load_dword v250, v[172:173], off offset:192
	global_load_dword v251, v[172:173], off offset:512
	global_load_dword v143, v[172:173], off offset:576
	global_load_dword v145, v[172:173], off offset:640
	global_load_dword v147, v[172:173], off offset:704
	s_and_b64 s[0:1], vcc, exec
	s_movk_i32 s0, 0x180
	s_cselect_b32 s0, s0, 0x80
	s_and_b32 s1, s4, 0x3fc0
	s_add_u32 s4, s82, s1
	s_addc_u32 s5, s83, 0
	v_readlane_b32 s49, v252, 3
	v_readlane_b32 s54, v252, 8
	v_readlane_b32 s55, v252, 9
	v_readlane_b32 s56, v252, 10
	v_readlane_b32 s57, v252, 11
	v_readlane_b32 s58, v252, 12
	v_readlane_b32 s59, v252, 13
	v_readlane_b32 s60, v252, 14
	v_readlane_b32 s61, v252, 15
	v_readlane_b32 s62, v252, 16
	v_readlane_b32 s63, v252, 17
	s_waitcnt vmcnt(0)
	v_fmamk_f32 v130, v130, 0x3a800000, v227
	v_cmp_gt_f32_e32 vcc, s36, v130
	v_mul_f32_e32 v131, 0x4b800000, v130
	s_nop 0
	v_cndmask_b32_e32 v130, v130, v131, vcc
	v_rsq_f32_e32 v130, v130
	s_nop 0
	v_mul_f32_e32 v131, 0x45800000, v130
	v_cndmask_b32_e32 v188, v130, v131, vcc
	global_load_dwordx4 v[130:133], v[166:167], off offset:16
	global_load_dwordx4 v[134:137], v[166:167], off
	s_waitcnt vmcnt(1)
	v_pk_fma_f32 v[140:141], v[122:123], v[188:189], v[132:133] op_sel_hi:[1,0,1]
	s_waitcnt vmcnt(0)
	v_pk_fma_f32 v[192:193], v[124:125], v[188:189], v[134:135] op_sel_hi:[1,0,1]
	v_pk_fma_f32 v[194:195], v[126:127], v[188:189], v[136:137] op_sel_hi:[1,0,1]
	v_pk_mul_f32 v[136:137], v[192:193], v[192:193]
	v_pk_mul_f32 v[134:135], v[194:195], v[194:195]
	s_nop 0
	v_pk_mov_b32 v[138:139], v[136:137], v[134:135] op_sel:[1,0]
	v_mov_b32_e32 v137, v135
	v_pk_add_f32 v[134:135], v[138:139], v[136:137]
	v_pk_fma_f32 v[138:139], v[120:121], v[188:189], v[130:131] op_sel_hi:[1,0,1]
	v_pk_mul_f32 v[130:131], v[140:141], v[140:141]
	v_pk_mul_f32 v[132:133], v[138:139], v[138:139]
	v_pk_add_f32 v[198:199], v[134:135], v[134:135] op_sel_hi:[0,1]
	v_pk_mov_b32 v[134:135], v[132:133], v[130:131] op_sel:[1,0]
	v_mov_b32_e32 v133, v131
	v_pk_add_f32 v[130:131], v[134:135], v[132:133]
	s_nop 0
	v_pk_add_f32 v[200:201], v[130:131], v[130:131] op_sel_hi:[0,1]
	global_load_dwordx4 v[130:133], v[166:167], off offset:528
	global_load_dwordx4 v[134:137], v[166:167], off offset:512
	s_waitcnt vmcnt(1)
	v_pk_fma_f32 v[190:191], v[58:59], v[188:189], v[132:133] op_sel_hi:[1,0,1]
	s_waitcnt vmcnt(0)
	v_pk_fma_f32 v[206:207], v[60:61], v[188:189], v[134:135] op_sel_hi:[1,0,1]
	v_pk_fma_f32 v[204:205], v[62:63], v[188:189], v[136:137] op_sel_hi:[1,0,1]
	v_mul_f32_e32 v134, v206, v206
	v_pk_fma_f32 v[134:135], v[206:207], v[206:207], v[134:135] op_sel_hi:[1,1,0]
	v_pk_fma_f32 v[196:197], v[56:57], v[188:189], v[130:131] op_sel_hi:[1,0,1]
	v_mul_f32_e32 v134, v204, v204
	v_pk_fma_f32 v[136:137], v[204:205], v[204:205], v[134:135] op_sel_hi:[1,1,0]
	v_mul_f32_e32 v134, v196, v196
	v_mul_f32_e32 v136, v197, v197
	v_mul_f32_e32 v198, v190, v190
	v_mul_f32_e32 v200, v191, v191
	v_pk_add_f32 v[130:131], v[134:135], v[136:137]
	v_pk_add_f32 v[132:133], v[198:199], v[200:201]
	v_lshl_add_u64 v[200:201], s[4:5], 0, v[186:187]
	v_pk_add_f32 v[130:131], v[130:131], v[132:133]
	s_add_u32 s4, s84, s1
	v_add_f32_e32 v130, v130, v131
	ds_bpermute_b32 v131, v246, v130
	s_addc_u32 s5, s85, 0
	v_lshl_add_u64 v[202:203], s[4:5], 0, v[186:187]
	global_load_dwordx4 v[134:137], v[200:201], off
	s_waitcnt lgkmcnt(0)
	v_add_f32_e32 v130, v130, v131
	ds_bpermute_b32 v131, v247, v130
	s_waitcnt lgkmcnt(0)
; __device__ __forceinline__ unsigned pk_bf16(float lo, float hi) { f32x2 v = {lo, hi}; bf16x2_t b = __builtin_convertvector(v, bf16x2_t); return __builtin_bit_cast(unsigned, b); }
;     __device__ __forceinline__ void operator()(const f32x4 (&acc)[2][2][4][2], const Unit& u, int wr, int wc, int fr, int fq) const {
;     ...
;                     ss += __shfl_xor(ss, 16); ss += __shfl_xor(ss, 32);
;                     const float rinv = rsqrtf(ss * (1.0f / 64.0f) + 1e-6f) * osc;
; #pragma unroll
;                     for (int bj = 0; bj < 2; ++bj) {
;                         const int pos = bj == 0 ? (t >> 6) : (t & 63);
;                         const f32x4 c = *(const f32x4*)(ropec + pos * 16 + 4 * fqo), s = *(const f32x4*)(ropes + pos * 16 + 4 * fqo);
;                         const f32x4 x1 = hv[bj][0] * rinv * *(const f32x4*)(gw + 32 * bj), x2 = hv[bj][1] * rinv * *(const f32x4*)(gw + 32 * bj + 16);
;                         const f32x4 o1 = x1 * c - x2 * s, o2 = x2 * c + x1 * s;
;                         u32x4 w; w.x = pk_bf16(o1[0], o1[1]); w.y = pk_bf16(o1[2], o1[3]); w.z = pk_bf16(o2[0], o2[1]); w.w = pk_bf16(o2[2], o2[3]);
;                         *(u32x4*)(base + (size_t)row * pitch + 32 * bj) = w;
	v_add_f32_e32 v130, v130, v131
	v_fmamk_f32 v130, v130, 0x3c800000, v227
	v_cmp_gt_f32_e32 vcc, s36, v130
	v_mul_f32_e32 v131, 0x4b800000, v130
	s_nop 0
	v_cndmask_b32_e32 v130, v130, v131, vcc
	v_rsq_f32_e32 v130, v130
	s_nop 0
	v_mul_f32_e32 v131, 0x45800000, v130
	v_cndmask_b32_e32 v130, v130, v131, vcc
	v_mul_f32_e32 v198, v245, v130
	v_pk_mul_f32 v[208:209], v[194:195], v[198:199] op_sel_hi:[1,0]
	v_pk_mul_f32 v[210:211], v[192:193], v[198:199] op_sel_hi:[1,0]
	global_load_dwordx4 v[192:195], v[168:169], off
	v_mad_i64_i32 v[130:131], s[6:7], s0, v162, 0
	v_lshl_add_u64 v[188:189], v[130:131], 1, v[170:171]
	global_load_dwordx4 v[130:133], v[202:203], off
	v_pk_mul_f32 v[204:205], v[204:205], v[198:199] op_sel_hi:[1,0]
	v_pk_mul_f32 v[206:207], v[206:207], v[198:199] op_sel_hi:[1,0]
	v_pk_mul_f32 v[196:197], v[196:197], v[198:199] op_sel_hi:[1,0]
	v_pk_mul_f32 v[190:191], v[190:191], v[198:199] op_sel_hi:[1,0]
	s_waitcnt vmcnt(1)
	v_pk_mul_f32 v[192:193], v[192:193], v[210:211]
	v_pk_mul_f32 v[194:195], v[194:195], v[208:209]
	v_pk_mul_f32 v[208:209], v[138:139], v[198:199] op_sel_hi:[1,0]
	v_pk_mul_f32 v[210:211], v[140:141], v[198:199] op_sel_hi:[1,0]
	global_load_dwordx4 v[138:141], v[168:169], off offset:64
	s_waitcnt vmcnt(0)
	v_pk_mul_f32 v[140:141], v[140:141], v[210:211]
	v_pk_mul_f32 v[138:139], v[138:139], v[208:209]
	v_pk_mul_f32 v[210:211], v[132:133], v[140:141]
	v_pk_mul_f32 v[208:209], v[130:131], v[138:139]
	v_pk_fma_f32 v[210:211], v[136:137], v[194:195], v[210:211] neg_lo:[0,0,1] neg_hi:[0,0,1]
	v_pk_fma_f32 v[208:209], v[134:135], v[192:193], v[208:209] neg_lo:[0,0,1] neg_hi:[0,0,1]
	v_pk_mul_f32 v[134:135], v[134:135], v[138:139]
	v_pk_mul_f32 v[136:137], v[136:137], v[140:141]
	s_nop 0
	v_pk_fma_f32 v[136:137], v[132:133], v[194:195], v[136:137]
	v_pk_fma_f32 v[132:133], v[130:131], v[192:193], v[134:135]
	v_cvt_pk_bf16_f32 v130, v208, v209
	v_cvt_pk_bf16_f32 v131, v210, v211
	v_cvt_pk_bf16_f32 v132, v132, v133
	v_cvt_pk_bf16_f32 v133, v136, v137
	global_store_dwordx4 v[188:189], v[130:133], off
	global_load_dwordx4 v[138:141], v[168:169], off offset:128
	v_lshl_add_u64 v[192:193], v[150:151], 0, v[186:187]
	v_lshl_add_u64 v[194:195], v[152:153], 0, v[186:187]
	global_load_dwordx4 v[130:133], v[192:193], off
	global_load_dwordx4 v[134:137], v[194:195], off
	s_waitcnt vmcnt(2)
	v_pk_mul_f32 v[206:207], v[138:139], v[206:207]
	v_pk_mul_f32 v[204:205], v[140:141], v[204:205]
	global_load_dwordx4 v[138:141], v[168:169], off offset:192
	s_waitcnt vmcnt(0)
	v_pk_mul_f32 v[140:141], v[140:141], v[190:191]
	v_pk_mul_f32 v[138:139], v[138:139], v[196:197]
	v_pk_mul_f32 v[196:197], v[136:137], v[140:141]
	v_pk_mul_f32 v[190:191], v[134:135], v[138:139]
	v_pk_fma_f32 v[196:197], v[132:133], v[204:205], v[196:197] neg_lo:[0,0,1] neg_hi:[0,0,1]
	v_pk_fma_f32 v[190:191], v[130:131], v[206:207], v[190:191] neg_lo:[0,0,1] neg_hi:[0,0,1]
	v_pk_mul_f32 v[130:131], v[130:131], v[138:139]
	v_pk_mul_f32 v[132:133], v[132:133], v[140:141]
	s_nop 0
	v_pk_fma_f32 v[136:137], v[136:137], v[204:205], v[132:133]
	v_pk_fma_f32 v[132:133], v[134:135], v[206:207], v[130:131]
	v_cvt_pk_bf16_f32 v130, v190, v191
	v_cvt_pk_bf16_f32 v131, v196, v197
	v_cvt_pk_bf16_f32 v132, v132, v133
	v_cvt_pk_bf16_f32 v133, v136, v137
	global_store_dwordx4 v[188:189], v[130:133], off offset:64
	s_nop 1
	v_fmamk_f32 v130, v248, 0x3a800000, v227
	v_cmp_gt_f32_e32 vcc, s36, v130
	v_mul_f32_e32 v131, 0x4b800000, v130
	s_nop 0
	v_cndmask_b32_e32 v130, v130, v131, vcc
	v_rsq_f32_e32 v130, v130
	s_nop 0
	v_mul_f32_e32 v131, 0x45800000, v130
	v_cndmask_b32_e32 v188, v130, v131, vcc
	global_load_dwordx4 v[130:133], v[166:167], off offset:16
	global_load_dwordx4 v[134:137], v[166:167], off
	s_waitcnt vmcnt(1)
	v_pk_fma_f32 v[130:131], v[112:113], v[188:189], v[130:131] op_sel_hi:[1,0,1]
	s_waitcnt vmcnt(0)
	v_pk_fma_f32 v[190:191], v[116:117], v[188:189], v[134:135] op_sel_hi:[1,0,1]
	v_pk_fma_f32 v[212:213], v[118:119], v[188:189], v[136:137] op_sel_hi:[1,0,1]
	v_pk_mul_f32 v[136:137], v[190:191], v[190:191]
	v_pk_mul_f32 v[134:135], v[212:213], v[212:213]
	v_pk_fma_f32 v[132:133], v[114:115], v[188:189], v[132:133] op_sel_hi:[1,0,1]
	v_pk_mov_b32 v[138:139], v[136:137], v[134:135] op_sel:[1,0]
	v_mov_b32_e32 v137, v135
	v_pk_add_f32 v[134:135], v[138:139], v[136:137]
	v_pk_mul_f32 v[136:137], v[130:131], v[130:131]
	v_pk_add_f32 v[196:197], v[134:135], v[134:135] op_sel_hi:[0,1]
	v_pk_mul_f32 v[134:135], v[132:133], v[132:133]
	s_nop 0
	v_pk_mov_b32 v[138:139], v[136:137], v[134:135] op_sel:[1,0]
	v_mov_b32_e32 v137, v135
	v_pk_add_f32 v[134:135], v[138:139], v[136:137]
	s_nop 0
	v_pk_add_f32 v[206:207], v[134:135], v[134:135] op_sel_hi:[0,1]
	global_load_dwordx4 v[134:137], v[166:167], off offset:528
	global_load_dwordx4 v[138:141], v[166:167], off offset:512
	s_waitcnt vmcnt(1)
	v_pk_fma_f32 v[198:199], v[50:51], v[188:189], v[136:137] op_sel_hi:[1,0,1]
	s_waitcnt vmcnt(0)
	v_pk_fma_f32 v[210:211], v[52:53], v[188:189], v[138:139] op_sel_hi:[1,0,1]
	v_pk_fma_f32 v[208:209], v[54:55], v[188:189], v[140:141] op_sel_hi:[1,0,1]
	v_mul_f32_e32 v138, v210, v210
	v_pk_fma_f32 v[138:139], v[210:211], v[210:211], v[138:139] op_sel_hi:[1,1,0]
	v_pk_fma_f32 v[204:205], v[48:49], v[188:189], v[134:135] op_sel_hi:[1,0,1]
	v_mul_f32_e32 v138, v208, v208
	v_pk_fma_f32 v[140:141], v[208:209], v[208:209], v[138:139] op_sel_hi:[1,1,0]
	v_mul_f32_e32 v138, v204, v204
	v_mul_f32_e32 v140, v205, v205
	v_mul_f32_e32 v196, v198, v198
	v_mul_f32_e32 v206, v199, v199
	v_pk_add_f32 v[134:135], v[138:139], v[140:141]
	v_pk_add_f32 v[136:137], v[196:197], v[206:207]
	s_nop 0
	v_pk_add_f32 v[134:135], v[134:135], v[136:137]
	s_nop 0
	v_add_f32_e32 v134, v134, v135
	ds_bpermute_b32 v135, v246, v134
	s_waitcnt lgkmcnt(0)
; __device__ __forceinline__ unsigned pk_bf16(float lo, float hi) { f32x2 v = {lo, hi}; bf16x2_t b = __builtin_convertvector(v, bf16x2_t); return __builtin_bit_cast(unsigned, b); }
;     __device__ __forceinline__ void operator()(const f32x4 (&acc)[2][2][4][2], const Unit& u, int wr, int wc, int fr, int fq) const {
;     ...
;                     ss += __shfl_xor(ss, 16); ss += __shfl_xor(ss, 32);
;                     const float rinv = rsqrtf(ss * (1.0f / 64.0f) + 1e-6f) * osc;
; #pragma unroll
;                     for (int bj = 0; bj < 2; ++bj) {
;                         const int pos = bj == 0 ? (t >> 6) : (t & 63);
;                         const f32x4 c = *(const f32x4*)(ropec + pos * 16 + 4 * fqo), s = *(const f32x4*)(ropes + pos * 16 + 4 * fqo);
;                         const f32x4 x1 = hv[bj][0] * rinv * *(const f32x4*)(gw + 32 * bj), x2 = hv[bj][1] * rinv * *(const f32x4*)(gw + 32 * bj + 16);
;                         const f32x4 o1 = x1 * c - x2 * s, o2 = x2 * c + x1 * s;
;                         u32x4 w; w.x = pk_bf16(o1[0], o1[1]); w.y = pk_bf16(o1[2], o1[3]); w.z = pk_bf16(o2[0], o2[1]); w.w = pk_bf16(o2[2], o2[3]);
;                         *(u32x4*)(base + (size_t)row * pitch + 32 * bj) = w;
	v_add_f32_e32 v134, v134, v135
	ds_bpermute_b32 v135, v247, v134
	s_waitcnt lgkmcnt(0)
	v_add_f32_e32 v134, v134, v135
	v_fmamk_f32 v134, v134, 0x3c800000, v227
	v_cmp_gt_f32_e32 vcc, s36, v134
	v_mul_f32_e32 v135, 0x4b800000, v134
	s_nop 0
	v_cndmask_b32_e32 v134, v134, v135, vcc
	v_rsq_f32_e32 v134, v134
	s_nop 0
	v_mul_f32_e32 v135, 0x45800000, v134
	v_cndmask_b32_e32 v134, v134, v135, vcc
	v_mul_f32_e32 v206, v245, v134
	v_mad_i64_i32 v[134:135], s[4:5], s0, v243, 0
	v_lshl_add_u64 v[196:197], v[134:135], 1, v[170:171]
	global_load_dwordx4 v[134:137], v[200:201], off
	global_load_dwordx4 v[138:141], v[202:203], off
	v_pk_mul_f32 v[214:215], v[190:191], v[206:207] op_sel_hi:[1,0]
	global_load_dwordx4 v[188:191], v[168:169], off
	v_pk_mul_f32 v[212:213], v[212:213], v[206:207] op_sel_hi:[1,0]
	v_pk_mul_f32 v[198:199], v[198:199], v[206:207] op_sel_hi:[1,0]
	s_waitcnt vmcnt(0)
	v_pk_mul_f32 v[188:189], v[188:189], v[214:215]
	v_pk_mul_f32 v[190:191], v[190:191], v[212:213]
	v_pk_mul_f32 v[212:213], v[130:131], v[206:207] op_sel_hi:[1,0]
	v_pk_mul_f32 v[214:215], v[132:133], v[206:207] op_sel_hi:[1,0]
	global_load_dwordx4 v[130:133], v[168:169], off offset:64
	s_waitcnt vmcnt(0)
	v_pk_mul_f32 v[132:133], v[132:133], v[214:215]
	v_pk_mul_f32 v[130:131], v[130:131], v[212:213]
	v_pk_mul_f32 v[214:215], v[140:141], v[132:133]
	v_pk_mul_f32 v[212:213], v[138:139], v[130:131]
	v_pk_mul_f32 v[130:131], v[134:135], v[130:131]
	v_pk_mul_f32 v[132:133], v[136:137], v[132:133]
	v_pk_fma_f32 v[214:215], v[136:137], v[190:191], v[214:215] neg_lo:[0,0,1] neg_hi:[0,0,1]
	v_pk_fma_f32 v[212:213], v[134:135], v[188:189], v[212:213] neg_lo:[0,0,1] neg_hi:[0,0,1]
	v_pk_fma_f32 v[134:135], v[140:141], v[190:191], v[132:133]
	v_pk_fma_f32 v[132:133], v[138:139], v[188:189], v[130:131]
	v_cvt_pk_bf16_f32 v130, v212, v213
	v_cvt_pk_bf16_f32 v131, v214, v215
	v_cvt_pk_bf16_f32 v132, v132, v133
	v_cvt_pk_bf16_f32 v133, v134, v135
	global_store_dwordx4 v[196:197], v[130:133], off
	v_pk_mul_f32 v[212:213], v[208:209], v[206:207] op_sel_hi:[1,0]
	v_pk_mul_f32 v[214:215], v[210:211], v[206:207] op_sel_hi:[1,0]
	global_load_dwordx4 v[208:211], v[168:169], off offset:128
	v_lshl_add_u64 v[138:139], s[82:83], 0, v[186:187]
	v_lshl_add_u64 v[140:141], s[84:85], 0, v[186:187]
	v_lshl_add_u64 v[188:189], v[138:139], 0, v[128:129]
	v_lshl_add_u64 v[190:191], v[140:141], 0, v[128:129]
	global_load_dwordx4 v[134:137], v[188:189], off
	global_load_dwordx4 v[130:133], v[190:191], off
	s_waitcnt vmcnt(2)
	v_pk_mul_f32 v[210:211], v[210:211], v[212:213]
	v_pk_mul_f32 v[212:213], v[204:205], v[206:207] op_sel_hi:[1,0]
	global_load_dwordx4 v[204:207], v[168:169], off offset:192
	v_pk_mul_f32 v[208:209], v[208:209], v[214:215]
	s_waitcnt vmcnt(0)
	v_pk_mul_f32 v[198:199], v[206:207], v[198:199]
	v_pk_mul_f32 v[204:205], v[204:205], v[212:213]
	v_pk_mul_f32 v[212:213], v[132:133], v[198:199]
	v_pk_mul_f32 v[206:207], v[130:131], v[204:205]
	v_pk_fma_f32 v[212:213], v[136:137], v[210:211], v[212:213] neg_lo:[0,0,1] neg_hi:[0,0,1]
	v_pk_fma_f32 v[206:207], v[134:135], v[208:209], v[206:207] neg_lo:[0,0,1] neg_hi:[0,0,1]
	v_pk_mul_f32 v[134:135], v[134:135], v[204:205]
	v_pk_mul_f32 v[136:137], v[136:137], v[198:199]
	s_nop 0
	v_pk_fma_f32 v[136:137], v[132:133], v[210:211], v[136:137]
	v_pk_fma_f32 v[132:133], v[130:131], v[208:209], v[134:135]
	v_cvt_pk_bf16_f32 v130, v206, v207
	v_cvt_pk_bf16_f32 v131, v212, v213
	v_cvt_pk_bf16_f32 v132, v132, v133
	v_cvt_pk_bf16_f32 v133, v136, v137
	global_store_dwordx4 v[196:197], v[130:133], off offset:64
	s_nop 1
	v_fmamk_f32 v130, v249, 0x3a800000, v227
	v_cmp_gt_f32_e32 vcc, s36, v130
	v_mul_f32_e32 v131, 0x4b800000, v130
	s_nop 0
	v_cndmask_b32_e32 v130, v130, v131, vcc
	v_rsq_f32_e32 v130, v130
	s_nop 0
	v_mul_f32_e32 v131, 0x45800000, v130
	v_cndmask_b32_e32 v196, v130, v131, vcc
	global_load_dwordx4 v[130:133], v[166:167], off offset:16
	global_load_dwordx4 v[134:137], v[166:167], off
	s_waitcnt vmcnt(1)
	v_pk_fma_f32 v[216:217], v[104:105], v[196:197], v[130:131] op_sel_hi:[1,0,1]
	s_waitcnt vmcnt(0)
	v_pk_fma_f32 v[198:199], v[108:109], v[196:197], v[134:135] op_sel_hi:[1,0,1]
	v_pk_fma_f32 v[220:221], v[110:111], v[196:197], v[136:137] op_sel_hi:[1,0,1]
	v_pk_mul_f32 v[136:137], v[198:199], v[198:199]
	v_pk_mul_f32 v[134:135], v[220:221], v[220:221]
	v_pk_fma_f32 v[218:219], v[106:107], v[196:197], v[132:133] op_sel_hi:[1,0,1]
	v_pk_mov_b32 v[204:205], v[136:137], v[134:135] op_sel:[1,0]
	v_mov_b32_e32 v137, v135
	v_pk_add_f32 v[134:135], v[204:205], v[136:137]
	v_pk_mul_f32 v[130:131], v[218:219], v[218:219]
	v_pk_mul_f32 v[132:133], v[216:217], v[216:217]
	v_pk_add_f32 v[204:205], v[134:135], v[134:135] op_sel_hi:[0,1]
	v_pk_mov_b32 v[134:135], v[132:133], v[130:131] op_sel:[1,0]
	v_mov_b32_e32 v133, v131
	v_pk_add_f32 v[130:131], v[134:135], v[132:133]
	s_nop 0
	v_pk_add_f32 v[210:211], v[130:131], v[130:131] op_sel_hi:[0,1]
	global_load_dwordx4 v[130:133], v[166:167], off offset:528
	global_load_dwordx4 v[134:137], v[166:167], off offset:512
	s_waitcnt vmcnt(1)
	v_pk_fma_f32 v[206:207], v[42:43], v[196:197], v[132:133] op_sel_hi:[1,0,1]
	s_waitcnt vmcnt(0)
	v_pk_fma_f32 v[214:215], v[44:45], v[196:197], v[134:135] op_sel_hi:[1,0,1]
	v_pk_fma_f32 v[212:213], v[46:47], v[196:197], v[136:137] op_sel_hi:[1,0,1]
	v_mul_f32_e32 v134, v214, v214
	v_pk_fma_f32 v[134:135], v[214:215], v[214:215], v[134:135] op_sel_hi:[1,1,0]
	v_pk_fma_f32 v[208:209], v[40:41], v[196:197], v[130:131] op_sel_hi:[1,0,1]
	v_mul_f32_e32 v134, v212, v212
	v_pk_fma_f32 v[136:137], v[212:213], v[212:213], v[134:135] op_sel_hi:[1,1,0]
	v_mul_f32_e32 v134, v208, v208
	v_mul_f32_e32 v136, v209, v209
	v_mul_f32_e32 v204, v206, v206
	v_mul_f32_e32 v210, v207, v207
	v_pk_add_f32 v[130:131], v[134:135], v[136:137]
	v_pk_add_f32 v[132:133], v[204:205], v[210:211]
	s_nop 0
	v_pk_add_f32 v[130:131], v[130:131], v[132:133]
	s_nop 0
	v_add_f32_e32 v130, v130, v131
	ds_bpermute_b32 v131, v246, v130
	s_waitcnt lgkmcnt(0)
; __device__ __forceinline__ unsigned pk_bf16(float lo, float hi) { f32x2 v = {lo, hi}; bf16x2_t b = __builtin_convertvector(v, bf16x2_t); return __builtin_bit_cast(unsigned, b); }
;     __device__ __forceinline__ void operator()(const f32x4 (&acc)[2][2][4][2], const Unit& u, int wr, int wc, int fr, int fq) const {
;     ...
;                     ss += __shfl_xor(ss, 16); ss += __shfl_xor(ss, 32);
;                     const float rinv = rsqrtf(ss * (1.0f / 64.0f) + 1e-6f) * osc;
; #pragma unroll
;                     for (int bj = 0; bj < 2; ++bj) {
;                         const int pos = bj == 0 ? (t >> 6) : (t & 63);
;                         const f32x4 c = *(const f32x4*)(ropec + pos * 16 + 4 * fqo), s = *(const f32x4*)(ropes + pos * 16 + 4 * fqo);
;                         const f32x4 x1 = hv[bj][0] * rinv * *(const f32x4*)(gw + 32 * bj), x2 = hv[bj][1] * rinv * *(const f32x4*)(gw + 32 * bj + 16);
;                         const f32x4 o1 = x1 * c - x2 * s, o2 = x2 * c + x1 * s;
;                         u32x4 w; w.x = pk_bf16(o1[0], o1[1]); w.y = pk_bf16(o1[2], o1[3]); w.z = pk_bf16(o2[0], o2[1]); w.w = pk_bf16(o2[2], o2[3]);
;                         *(u32x4*)(base + (size_t)row * pitch + 32 * bj) = w;
	v_add_f32_e32 v130, v130, v131
	ds_bpermute_b32 v131, v247, v130
	s_waitcnt lgkmcnt(0)
	v_add_f32_e32 v130, v130, v131
	v_fmamk_f32 v130, v130, 0x3c800000, v227
	v_cmp_gt_f32_e32 vcc, s36, v130
	v_mul_f32_e32 v131, 0x4b800000, v130
	s_nop 0
	v_cndmask_b32_e32 v130, v130, v131, vcc
	v_rsq_f32_e32 v130, v130
	s_nop 0
	v_mul_f32_e32 v131, 0x45800000, v130
	v_cndmask_b32_e32 v130, v130, v131, vcc
	v_mul_f32_e32 v210, v245, v130
	v_mad_i64_i32 v[130:131], s[4:5], s0, v242, 0
	v_lshl_add_u64 v[204:205], v[130:131], 1, v[170:171]
	global_load_dwordx4 v[134:137], v[200:201], off
	global_load_dwordx4 v[130:133], v[202:203], off
	v_pk_mul_f32 v[222:223], v[198:199], v[210:211] op_sel_hi:[1,0]
	global_load_dwordx4 v[196:199], v[168:169], off
	v_pk_mul_f32 v[220:221], v[220:221], v[210:211] op_sel_hi:[1,0]
	v_pk_mul_f32 v[216:217], v[216:217], v[210:211] op_sel_hi:[1,0]
	v_pk_mul_f32 v[218:219], v[218:219], v[210:211] op_sel_hi:[1,0]
	s_waitcnt vmcnt(0)
	v_pk_mul_f32 v[196:197], v[196:197], v[222:223]
	v_pk_mul_f32 v[198:199], v[198:199], v[220:221]
	global_load_dwordx4 v[220:223], v[168:169], off offset:64
	s_waitcnt vmcnt(0)
	v_pk_mul_f32 v[218:219], v[222:223], v[218:219]
	v_pk_mul_f32 v[216:217], v[220:221], v[216:217]
	v_pk_mul_f32 v[222:223], v[132:133], v[218:219]
	v_pk_mul_f32 v[220:221], v[130:131], v[216:217]
	v_pk_fma_f32 v[222:223], v[136:137], v[198:199], v[222:223] neg_lo:[0,0,1] neg_hi:[0,0,1]
	v_pk_fma_f32 v[220:221], v[134:135], v[196:197], v[220:221] neg_lo:[0,0,1] neg_hi:[0,0,1]
	v_pk_mul_f32 v[134:135], v[134:135], v[216:217]
	v_pk_mul_f32 v[136:137], v[136:137], v[218:219]
	v_pk_mul_f32 v[216:217], v[212:213], v[210:211] op_sel_hi:[1,0]
	v_pk_fma_f32 v[136:137], v[132:133], v[198:199], v[136:137]
	v_pk_fma_f32 v[132:133], v[130:131], v[196:197], v[134:135]
	v_cvt_pk_bf16_f32 v130, v220, v221
	v_cvt_pk_bf16_f32 v131, v222, v223
	v_cvt_pk_bf16_f32 v132, v132, v133
	v_cvt_pk_bf16_f32 v133, v136, v137
	global_store_dwordx4 v[204:205], v[130:133], off
	v_pk_mul_f32 v[218:219], v[214:215], v[210:211] op_sel_hi:[1,0]
	global_load_dwordx4 v[212:215], v[168:169], off offset:128
	v_lshl_add_u64 v[196:197], v[138:139], 0, v[158:159]
	v_lshl_add_u64 v[198:199], v[140:141], 0, v[158:159]
	global_load_dwordx4 v[130:133], v[196:197], off
	global_load_dwordx4 v[134:137], v[198:199], off
	v_add_u32_e32 v159, 0x80, v162
	s_waitcnt vmcnt(2)
	v_pk_mul_f32 v[214:215], v[214:215], v[216:217]
	v_pk_mul_f32 v[216:217], v[208:209], v[210:211] op_sel_hi:[1,0]
	v_pk_mul_f32 v[210:211], v[206:207], v[210:211] op_sel_hi:[1,0]
	global_load_dwordx4 v[206:209], v[168:169], off offset:192
	v_pk_mul_f32 v[212:213], v[212:213], v[218:219]
	s_waitcnt vmcnt(0)
	v_pk_mul_f32 v[208:209], v[208:209], v[210:211]
	v_pk_mul_f32 v[206:207], v[206:207], v[216:217]
	v_pk_mul_f32 v[216:217], v[136:137], v[208:209]
	v_pk_mul_f32 v[210:211], v[134:135], v[206:207]
	v_pk_fma_f32 v[216:217], v[132:133], v[214:215], v[216:217] neg_lo:[0,0,1] neg_hi:[0,0,1]
	v_pk_fma_f32 v[210:211], v[130:131], v[212:213], v[210:211] neg_lo:[0,0,1] neg_hi:[0,0,1]
	v_pk_mul_f32 v[130:131], v[130:131], v[206:207]
	v_pk_mul_f32 v[132:133], v[132:133], v[208:209]
	s_nop 0
	v_pk_fma_f32 v[136:137], v[136:137], v[214:215], v[132:133]
	v_pk_fma_f32 v[132:133], v[134:135], v[212:213], v[130:131]
	v_cvt_pk_bf16_f32 v130, v210, v211
	v_cvt_pk_bf16_f32 v131, v216, v217
	v_cvt_pk_bf16_f32 v132, v132, v133
	v_cvt_pk_bf16_f32 v133, v136, v137
	global_store_dwordx4 v[204:205], v[130:133], off offset:64
	s_nop 1
	v_fmamk_f32 v130, v250, 0x3a800000, v227
	v_cmp_gt_f32_e32 vcc, s36, v130
	v_mul_f32_e32 v131, 0x4b800000, v130
	s_nop 0
	v_cndmask_b32_e32 v130, v130, v131, vcc
	v_rsq_f32_e32 v130, v130
	s_nop 0
	v_mul_f32_e32 v131, 0x45800000, v130
	v_cndmask_b32_e32 v204, v130, v131, vcc
	global_load_dwordx4 v[130:133], v[166:167], off offset:16
	global_load_dwordx4 v[134:137], v[166:167], off
	s_waitcnt vmcnt(1)
	v_pk_fma_f32 v[216:217], v[96:97], v[204:205], v[130:131] op_sel_hi:[1,0,1]
	s_waitcnt vmcnt(0)
	v_pk_fma_f32 v[220:221], v[100:101], v[204:205], v[134:135] op_sel_hi:[1,0,1]
	v_pk_fma_f32 v[222:223], v[102:103], v[204:205], v[136:137] op_sel_hi:[1,0,1]
	v_pk_mul_f32 v[136:137], v[220:221], v[220:221]
	v_pk_mul_f32 v[134:135], v[222:223], v[222:223]
	v_pk_fma_f32 v[218:219], v[98:99], v[204:205], v[132:133] op_sel_hi:[1,0,1]
	v_pk_mov_b32 v[206:207], v[136:137], v[134:135] op_sel:[1,0]
	v_mov_b32_e32 v137, v135
	v_pk_add_f32 v[134:135], v[206:207], v[136:137]
	v_pk_mul_f32 v[130:131], v[218:219], v[218:219]
	v_pk_mul_f32 v[132:133], v[216:217], v[216:217]
	v_pk_add_f32 v[210:211], v[134:135], v[134:135] op_sel_hi:[0,1]
	v_pk_mov_b32 v[134:135], v[132:133], v[130:131] op_sel:[1,0]
	v_mov_b32_e32 v133, v131
	v_pk_add_f32 v[130:131], v[134:135], v[132:133]
	s_nop 0
	v_pk_add_f32 v[224:225], v[130:131], v[130:131] op_sel_hi:[0,1]
	global_load_dwordx4 v[130:133], v[166:167], off offset:528
	global_load_dwordx4 v[134:137], v[166:167], off offset:512
	s_waitcnt vmcnt(1)
	v_pk_fma_f32 v[206:207], v[34:35], v[204:205], v[132:133] op_sel_hi:[1,0,1]
	s_waitcnt vmcnt(0)
	v_pk_fma_f32 v[214:215], v[36:37], v[204:205], v[134:135] op_sel_hi:[1,0,1]
	v_pk_fma_f32 v[212:213], v[38:39], v[204:205], v[136:137] op_sel_hi:[1,0,1]
	v_mul_f32_e32 v134, v214, v214
	v_pk_fma_f32 v[134:135], v[214:215], v[214:215], v[134:135] op_sel_hi:[1,1,0]
	v_pk_fma_f32 v[208:209], v[32:33], v[204:205], v[130:131] op_sel_hi:[1,0,1]
	v_mul_f32_e32 v134, v212, v212
	v_pk_fma_f32 v[136:137], v[212:213], v[212:213], v[134:135] op_sel_hi:[1,1,0]
	v_mul_f32_e32 v134, v208, v208
	v_mul_f32_e32 v136, v209, v209
	v_mul_f32_e32 v210, v206, v206
	v_mul_f32_e32 v224, v207, v207
	v_pk_add_f32 v[130:131], v[134:135], v[136:137]
	v_pk_add_f32 v[132:133], v[210:211], v[224:225]
	s_nop 0
	v_pk_add_f32 v[130:131], v[130:131], v[132:133]
	s_nop 0
	v_add_f32_e32 v130, v130, v131
	ds_bpermute_b32 v131, v246, v130
	s_waitcnt lgkmcnt(0)
; __device__ __forceinline__ unsigned pk_bf16(float lo, float hi) { f32x2 v = {lo, hi}; bf16x2_t b = __builtin_convertvector(v, bf16x2_t); return __builtin_bit_cast(unsigned, b); }
;     __device__ __forceinline__ void operator()(const f32x4 (&acc)[2][2][4][2], const Unit& u, int wr, int wc, int fr, int fq) const {
;     ...
;                     ss += __shfl_xor(ss, 16); ss += __shfl_xor(ss, 32);
;                     const float rinv = rsqrtf(ss * (1.0f / 64.0f) + 1e-6f) * osc;
; #pragma unroll
;                     for (int bj = 0; bj < 2; ++bj) {
;                         const int pos = bj == 0 ? (t >> 6) : (t & 63);
;                         const f32x4 c = *(const f32x4*)(ropec + pos * 16 + 4 * fqo), s = *(const f32x4*)(ropes + pos * 16 + 4 * fqo);
;                         const f32x4 x1 = hv[bj][0] * rinv * *(const f32x4*)(gw + 32 * bj), x2 = hv[bj][1] * rinv * *(const f32x4*)(gw + 32 * bj + 16);
;                         const f32x4 o1 = x1 * c - x2 * s, o2 = x2 * c + x1 * s;
;                         u32x4 w; w.x = pk_bf16(o1[0], o1[1]); w.y = pk_bf16(o1[2], o1[3]); w.z = pk_bf16(o2[0], o2[1]); w.w = pk_bf16(o2[2], o2[3]);
;                         *(u32x4*)(base + (size_t)row * pitch + 32 * bj) = w;
	v_add_f32_e32 v130, v130, v131
	ds_bpermute_b32 v131, v247, v130
	s_waitcnt lgkmcnt(0)
	v_add_f32_e32 v130, v130, v131
	v_fmamk_f32 v130, v130, 0x3c800000, v227
	v_cmp_gt_f32_e32 vcc, s36, v130
	v_mul_f32_e32 v131, 0x4b800000, v130
	s_nop 0
	v_cndmask_b32_e32 v130, v130, v131, vcc
	v_rsq_f32_e32 v130, v130
	s_nop 0
	v_mul_f32_e32 v131, 0x45800000, v130
	v_cndmask_b32_e32 v130, v130, v131, vcc
	v_mul_f32_e32 v210, v245, v130
	v_mad_i64_i32 v[130:131], s[4:5], s0, v241, 0
	v_lshl_add_u64 v[204:205], v[130:131], 1, v[170:171]
	global_load_dwordx4 v[134:137], v[200:201], off
	global_load_dwordx4 v[130:133], v[202:203], off
	v_pk_mul_f32 v[222:223], v[222:223], v[210:211] op_sel_hi:[1,0]
	global_load_dwordx4 v[200:203], v[168:169], off
	v_pk_mul_f32 v[220:221], v[220:221], v[210:211] op_sel_hi:[1,0]
	v_pk_mul_f32 v[216:217], v[216:217], v[210:211] op_sel_hi:[1,0]
	v_pk_mul_f32 v[218:219], v[218:219], v[210:211] op_sel_hi:[1,0]
	v_pk_mul_f32 v[212:213], v[212:213], v[210:211] op_sel_hi:[1,0]
	v_pk_mul_f32 v[214:215], v[214:215], v[210:211] op_sel_hi:[1,0]
	v_pk_mul_f32 v[208:209], v[208:209], v[210:211] op_sel_hi:[1,0]
	v_pk_mul_f32 v[206:207], v[206:207], v[210:211] op_sel_hi:[1,0]
	s_waitcnt vmcnt(0)
	v_pk_mul_f32 v[200:201], v[200:201], v[220:221]
	v_pk_mul_f32 v[202:203], v[202:203], v[222:223]
	global_load_dwordx4 v[220:223], v[168:169], off offset:64
	s_waitcnt vmcnt(0)
	v_pk_mul_f32 v[218:219], v[222:223], v[218:219]
	v_pk_mul_f32 v[216:217], v[220:221], v[216:217]
	v_pk_mul_f32 v[222:223], v[132:133], v[218:219]
	v_pk_mul_f32 v[220:221], v[130:131], v[216:217]
	v_pk_fma_f32 v[222:223], v[136:137], v[202:203], v[222:223] neg_lo:[0,0,1] neg_hi:[0,0,1]
	v_pk_fma_f32 v[220:221], v[134:135], v[200:201], v[220:221] neg_lo:[0,0,1] neg_hi:[0,0,1]
	v_pk_mul_f32 v[134:135], v[134:135], v[216:217]
	v_pk_mul_f32 v[136:137], v[136:137], v[218:219]
	s_nop 0
	v_pk_fma_f32 v[136:137], v[132:133], v[202:203], v[136:137]
	v_pk_fma_f32 v[132:133], v[130:131], v[200:201], v[134:135]
	v_cvt_pk_bf16_f32 v130, v220, v221
	v_cvt_pk_bf16_f32 v131, v222, v223
	v_cvt_pk_bf16_f32 v132, v132, v133
	v_cvt_pk_bf16_f32 v133, v136, v137
	global_store_dwordx4 v[204:205], v[130:133], off
	v_lshl_add_u64 v[200:201], v[138:139], 0, v[160:161]
	v_lshl_add_u64 v[202:203], v[140:141], 0, v[160:161]
	global_load_dwordx4 v[138:141], v[168:169], off offset:128
	global_load_dwordx4 v[130:133], v[200:201], off
	global_load_dwordx4 v[134:137], v[202:203], off
	s_waitcnt vmcnt(2)
	v_pk_mul_f32 v[214:215], v[138:139], v[214:215]
	v_pk_mul_f32 v[212:213], v[140:141], v[212:213]
	global_load_dwordx4 v[138:141], v[168:169], off offset:192
	s_waitcnt vmcnt(0)
	v_pk_mul_f32 v[140:141], v[140:141], v[206:207]
	v_pk_mul_f32 v[138:139], v[138:139], v[208:209]
	v_pk_mul_f32 v[208:209], v[136:137], v[140:141]
	v_pk_mul_f32 v[206:207], v[134:135], v[138:139]
	v_pk_fma_f32 v[208:209], v[132:133], v[212:213], v[208:209] neg_lo:[0,0,1] neg_hi:[0,0,1]
	v_pk_fma_f32 v[206:207], v[130:131], v[214:215], v[206:207] neg_lo:[0,0,1] neg_hi:[0,0,1]
	v_pk_mul_f32 v[130:131], v[130:131], v[138:139]
	v_pk_mul_f32 v[132:133], v[132:133], v[140:141]
	s_nop 0
	v_pk_fma_f32 v[136:137], v[136:137], v[212:213], v[132:133]
	v_pk_fma_f32 v[132:133], v[134:135], v[214:215], v[130:131]
	v_cvt_pk_bf16_f32 v130, v206, v207
	v_cvt_pk_bf16_f32 v131, v208, v209
	v_cvt_pk_bf16_f32 v132, v132, v133
	v_cvt_pk_bf16_f32 v133, v136, v137
	global_store_dwordx4 v[204:205], v[130:133], off offset:64
	s_nop 1
	v_fmamk_f32 v130, v251, 0x3a800000, v227
	v_cmp_gt_f32_e32 vcc, s36, v130
	v_mul_f32_e32 v131, 0x4b800000, v130
	s_nop 0
	v_cndmask_b32_e32 v130, v130, v131, vcc
	v_rsq_f32_e32 v130, v130
	s_nop 0
	v_mul_f32_e32 v131, 0x45800000, v130
	v_cndmask_b32_e32 v204, v130, v131, vcc
	global_load_dwordx4 v[130:133], v[166:167], off offset:16
	global_load_dwordx4 v[134:137], v[166:167], off
	s_waitcnt vmcnt(1)
	v_pk_fma_f32 v[140:141], v[90:91], v[204:205], v[132:133] op_sel_hi:[1,0,1]
	s_waitcnt vmcnt(0)
	v_pk_fma_f32 v[218:219], v[92:93], v[204:205], v[134:135] op_sel_hi:[1,0,1]
	v_pk_fma_f32 v[220:221], v[94:95], v[204:205], v[136:137] op_sel_hi:[1,0,1]
	v_pk_mul_f32 v[136:137], v[218:219], v[218:219]
	v_pk_mul_f32 v[134:135], v[220:221], v[220:221]
	s_nop 0
	v_pk_mov_b32 v[138:139], v[136:137], v[134:135] op_sel:[1,0]
	v_mov_b32_e32 v137, v135
	v_pk_add_f32 v[134:135], v[138:139], v[136:137]
	v_pk_fma_f32 v[138:139], v[88:89], v[204:205], v[130:131] op_sel_hi:[1,0,1]
	v_pk_mul_f32 v[130:131], v[140:141], v[140:141]
	v_pk_mul_f32 v[132:133], v[138:139], v[138:139]
	v_pk_add_f32 v[206:207], v[134:135], v[134:135] op_sel_hi:[0,1]
	v_pk_mov_b32 v[134:135], v[132:133], v[130:131] op_sel:[1,0]
	v_mov_b32_e32 v133, v131
	v_pk_add_f32 v[130:131], v[134:135], v[132:133]
	s_nop 0
	v_pk_add_f32 v[216:217], v[130:131], v[130:131] op_sel_hi:[0,1]
	global_load_dwordx4 v[130:133], v[166:167], off offset:528
	global_load_dwordx4 v[134:137], v[166:167], off offset:512
	s_waitcnt vmcnt(1)
	v_pk_fma_f32 v[208:209], v[26:27], v[204:205], v[132:133] op_sel_hi:[1,0,1]
	s_waitcnt vmcnt(0)
	v_pk_fma_f32 v[214:215], v[28:29], v[204:205], v[134:135] op_sel_hi:[1,0,1]
	v_pk_fma_f32 v[212:213], v[30:31], v[204:205], v[136:137] op_sel_hi:[1,0,1]
	v_mul_f32_e32 v134, v214, v214
	v_pk_fma_f32 v[134:135], v[214:215], v[214:215], v[134:135] op_sel_hi:[1,1,0]
	v_pk_fma_f32 v[210:211], v[24:25], v[204:205], v[130:131] op_sel_hi:[1,0,1]
	v_mul_f32_e32 v134, v212, v212
	v_pk_fma_f32 v[136:137], v[212:213], v[212:213], v[134:135] op_sel_hi:[1,1,0]
	v_mul_f32_e32 v134, v210, v210
	v_mul_f32_e32 v136, v211, v211
	v_mul_f32_e32 v206, v208, v208
	v_mul_f32_e32 v216, v209, v209
	v_pk_add_f32 v[130:131], v[134:135], v[136:137]
	v_pk_add_f32 v[132:133], v[206:207], v[216:217]
	s_nop 0
	v_pk_add_f32 v[130:131], v[130:131], v[132:133]
	s_nop 0
	v_add_f32_e32 v130, v130, v131
	ds_bpermute_b32 v131, v246, v130
	s_waitcnt lgkmcnt(0)
; __device__ __forceinline__ unsigned pk_bf16(float lo, float hi) { f32x2 v = {lo, hi}; bf16x2_t b = __builtin_convertvector(v, bf16x2_t); return __builtin_bit_cast(unsigned, b); }
;     __device__ __forceinline__ void operator()(const f32x4 (&acc)[2][2][4][2], const Unit& u, int wr, int wc, int fr, int fq) const {
;     ...
;                     ss += __shfl_xor(ss, 16); ss += __shfl_xor(ss, 32);
;                     const float rinv = rsqrtf(ss * (1.0f / 64.0f) + 1e-6f) * osc;
; #pragma unroll
;                     for (int bj = 0; bj < 2; ++bj) {
;                         const int pos = bj == 0 ? (t >> 6) : (t & 63);
;                         const f32x4 c = *(const f32x4*)(ropec + pos * 16 + 4 * fqo), s = *(const f32x4*)(ropes + pos * 16 + 4 * fqo);
;                         const f32x4 x1 = hv[bj][0] * rinv * *(const f32x4*)(gw + 32 * bj), x2 = hv[bj][1] * rinv * *(const f32x4*)(gw + 32 * bj + 16);
;                         const f32x4 o1 = x1 * c - x2 * s, o2 = x2 * c + x1 * s;
;                         u32x4 w; w.x = pk_bf16(o1[0], o1[1]); w.y = pk_bf16(o1[2], o1[3]); w.z = pk_bf16(o2[0], o2[1]); w.w = pk_bf16(o2[2], o2[3]);
;                         *(u32x4*)(base + (size_t)row * pitch + 32 * bj) = w;
	v_add_f32_e32 v130, v130, v131
	ds_bpermute_b32 v131, v247, v130
	s_waitcnt lgkmcnt(0)
	v_add_f32_e32 v130, v130, v131
	v_fmamk_f32 v130, v130, 0x3c800000, v227
	v_cmp_gt_f32_e32 vcc, s36, v130
	v_mul_f32_e32 v131, 0x4b800000, v130
	s_nop 0
	v_cndmask_b32_e32 v130, v130, v131, vcc
	v_rsq_f32_e32 v130, v130
	s_nop 0
	v_mul_f32_e32 v131, 0x45800000, v130
	v_cndmask_b32_e32 v130, v130, v131, vcc
	v_mul_f32_e32 v216, v245, v130
	v_pk_mul_f32 v[222:223], v[220:221], v[216:217] op_sel_hi:[1,0]
	v_pk_mul_f32 v[224:225], v[218:219], v[216:217] op_sel_hi:[1,0]
	global_load_dwordx4 v[218:221], v[168:169], off
	v_mad_i64_i32 v[130:131], s[4:5], s0, v159, 0
	v_lshl_add_u64 v[206:207], v[130:131], 1, v[170:171]
	v_and_b32_e32 v130, 0x3fc0, v159
	v_mov_b32_e32 v131, v129
	v_lshl_add_u64 v[132:133], s[82:83], 0, v[130:131]
	v_lshl_add_u64 v[130:131], s[84:85], 0, v[130:131]
	v_lshl_add_u64 v[204:205], v[132:133], 0, v[186:187]
	v_lshl_add_u64 v[186:187], v[130:131], 0, v[186:187]
	global_load_dwordx4 v[134:137], v[204:205], off
	global_load_dwordx4 v[130:133], v[186:187], off
	v_pk_mul_f32 v[210:211], v[210:211], v[216:217] op_sel_hi:[1,0]
	v_pk_mul_f32 v[208:209], v[208:209], v[216:217] op_sel_hi:[1,0]
	v_add_u32_e32 v159, 0x90, v162
	s_waitcnt vmcnt(2)
	v_pk_mul_f32 v[218:219], v[218:219], v[224:225]
	v_pk_mul_f32 v[220:221], v[220:221], v[222:223]
	v_pk_mul_f32 v[222:223], v[138:139], v[216:217] op_sel_hi:[1,0]
	v_pk_mul_f32 v[224:225], v[140:141], v[216:217] op_sel_hi:[1,0]
	global_load_dwordx4 v[138:141], v[168:169], off offset:64
	s_waitcnt vmcnt(0)
	v_pk_mul_f32 v[140:141], v[140:141], v[224:225]
	v_pk_mul_f32 v[138:139], v[138:139], v[222:223]
	v_pk_mul_f32 v[224:225], v[132:133], v[140:141]
	v_pk_mul_f32 v[222:223], v[130:131], v[138:139]
	v_pk_fma_f32 v[224:225], v[136:137], v[220:221], v[224:225] neg_lo:[0,0,1] neg_hi:[0,0,1]
	v_pk_fma_f32 v[222:223], v[134:135], v[218:219], v[222:223] neg_lo:[0,0,1] neg_hi:[0,0,1]
	v_pk_mul_f32 v[134:135], v[134:135], v[138:139]
	v_pk_mul_f32 v[136:137], v[136:137], v[140:141]
	s_nop 0
	v_pk_fma_f32 v[136:137], v[132:133], v[220:221], v[136:137]
	v_pk_fma_f32 v[132:133], v[130:131], v[218:219], v[134:135]
	v_cvt_pk_bf16_f32 v130, v222, v223
	v_cvt_pk_bf16_f32 v131, v224, v225
	v_cvt_pk_bf16_f32 v132, v132, v133
	v_cvt_pk_bf16_f32 v133, v136, v137
	global_store_dwordx4 v[206:207], v[130:133], off
	global_load_dwordx4 v[130:133], v[192:193], off
	s_nop 0
	global_load_dwordx4 v[134:137], v[194:195], off
	global_load_dwordx4 v[138:141], v[168:169], off offset:128
	v_pk_mul_f32 v[192:193], v[212:213], v[216:217] op_sel_hi:[1,0]
	v_pk_mul_f32 v[194:195], v[214:215], v[216:217] op_sel_hi:[1,0]
	s_waitcnt vmcnt(0)
	v_pk_mul_f32 v[192:193], v[140:141], v[192:193]
	v_pk_mul_f32 v[194:195], v[138:139], v[194:195]
	global_load_dwordx4 v[138:141], v[168:169], off offset:192
	s_waitcnt vmcnt(0)
	v_pk_mul_f32 v[140:141], v[140:141], v[208:209]
	v_pk_mul_f32 v[138:139], v[138:139], v[210:211]
	v_pk_mul_f32 v[210:211], v[136:137], v[140:141]
	v_pk_mul_f32 v[208:209], v[134:135], v[138:139]
	v_pk_fma_f32 v[210:211], v[132:133], v[192:193], v[210:211] neg_lo:[0,0,1] neg_hi:[0,0,1]
	v_pk_fma_f32 v[208:209], v[130:131], v[194:195], v[208:209] neg_lo:[0,0,1] neg_hi:[0,0,1]
	v_pk_mul_f32 v[130:131], v[130:131], v[138:139]
	v_pk_mul_f32 v[132:133], v[132:133], v[140:141]
	s_nop 0
	v_pk_fma_f32 v[136:137], v[136:137], v[192:193], v[132:133]
	v_pk_fma_f32 v[132:133], v[134:135], v[194:195], v[130:131]
	v_cvt_pk_bf16_f32 v130, v208, v209
	v_cvt_pk_bf16_f32 v131, v210, v211
	v_cvt_pk_bf16_f32 v132, v132, v133
	v_cvt_pk_bf16_f32 v133, v136, v137
	global_store_dwordx4 v[206:207], v[130:133], off offset:64
	s_nop 1
	v_fmamk_f32 v130, v143, 0x3a800000, v227
	v_cmp_gt_f32_e32 vcc, s36, v130
	v_mul_f32_e32 v131, 0x4b800000, v130
	s_nop 0
	v_cndmask_b32_e32 v130, v130, v131, vcc
	v_rsq_f32_e32 v130, v130
	s_nop 0
	v_mul_f32_e32 v131, 0x45800000, v130
	v_cndmask_b32_e32 v192, v130, v131, vcc
	global_load_dwordx4 v[130:133], v[166:167], off offset:16
	global_load_dwordx4 v[134:137], v[166:167], off
	s_waitcnt vmcnt(1)
	v_pk_fma_f32 v[140:141], v[82:83], v[192:193], v[132:133] op_sel_hi:[1,0,1]
	s_waitcnt vmcnt(0)
	v_pk_fma_f32 v[214:215], v[84:85], v[192:193], v[134:135] op_sel_hi:[1,0,1]
	v_pk_fma_f32 v[216:217], v[86:87], v[192:193], v[136:137] op_sel_hi:[1,0,1]
	v_pk_mul_f32 v[136:137], v[214:215], v[214:215]
	v_pk_mul_f32 v[134:135], v[216:217], v[216:217]
	s_nop 0
	v_pk_mov_b32 v[138:139], v[136:137], v[134:135] op_sel:[1,0]
	v_mov_b32_e32 v137, v135
	v_pk_add_f32 v[134:135], v[138:139], v[136:137]
	v_pk_fma_f32 v[138:139], v[80:81], v[192:193], v[130:131] op_sel_hi:[1,0,1]
	v_pk_mul_f32 v[130:131], v[140:141], v[140:141]
	v_pk_mul_f32 v[132:133], v[138:139], v[138:139]
	v_pk_add_f32 v[212:213], v[134:135], v[134:135] op_sel_hi:[0,1]
	v_pk_mov_b32 v[134:135], v[132:133], v[130:131] op_sel:[1,0]
	v_mov_b32_e32 v133, v131
	v_pk_add_f32 v[130:131], v[134:135], v[132:133]
	s_nop 0
	v_pk_add_f32 v[218:219], v[130:131], v[130:131] op_sel_hi:[0,1]
	global_load_dwordx4 v[130:133], v[166:167], off offset:528
	global_load_dwordx4 v[134:137], v[166:167], off offset:512
	s_waitcnt vmcnt(1)
	v_pk_fma_f32 v[194:195], v[18:19], v[192:193], v[132:133] op_sel_hi:[1,0,1]
	s_waitcnt vmcnt(0)
; __device__ __forceinline__ unsigned pk_bf16(float lo, float hi) { f32x2 v = {lo, hi}; bf16x2_t b = __builtin_convertvector(v, bf16x2_t); return __builtin_bit_cast(unsigned, b); }
;     __device__ __forceinline__ void operator()(const f32x4 (&acc)[2][2][4][2], const Unit& u, int wr, int wc, int fr, int fq) const {
;     ...
;                     ss += __shfl_xor(ss, 16); ss += __shfl_xor(ss, 32);
;                     const float rinv = rsqrtf(ss * (1.0f / 64.0f) + 1e-6f) * osc;
; #pragma unroll
;                     for (int bj = 0; bj < 2; ++bj) {
;                         const int pos = bj == 0 ? (t >> 6) : (t & 63);
;                         const f32x4 c = *(const f32x4*)(ropec + pos * 16 + 4 * fqo), s = *(const f32x4*)(ropes + pos * 16 + 4 * fqo);
;                         const f32x4 x1 = hv[bj][0] * rinv * *(const f32x4*)(gw + 32 * bj), x2 = hv[bj][1] * rinv * *(const f32x4*)(gw + 32 * bj + 16);
;                         const f32x4 o1 = x1 * c - x2 * s, o2 = x2 * c + x1 * s;
;                         u32x4 w; w.x = pk_bf16(o1[0], o1[1]); w.y = pk_bf16(o1[2], o1[3]); w.z = pk_bf16(o2[0], o2[1]); w.w = pk_bf16(o2[2], o2[3]);
;                         *(u32x4*)(base + (size_t)row * pitch + 32 * bj) = w;
	v_pk_fma_f32 v[210:211], v[20:21], v[192:193], v[134:135] op_sel_hi:[1,0,1]
	v_pk_fma_f32 v[208:209], v[22:23], v[192:193], v[136:137] op_sel_hi:[1,0,1]
	v_mul_f32_e32 v134, v210, v210
	v_pk_fma_f32 v[134:135], v[210:211], v[210:211], v[134:135] op_sel_hi:[1,1,0]
	v_pk_fma_f32 v[206:207], v[16:17], v[192:193], v[130:131] op_sel_hi:[1,0,1]
	v_mul_f32_e32 v134, v208, v208
	v_pk_fma_f32 v[136:137], v[208:209], v[208:209], v[134:135] op_sel_hi:[1,1,0]
	v_mul_f32_e32 v134, v206, v206
	v_mul_f32_e32 v136, v207, v207
	v_mul_f32_e32 v212, v194, v194
	v_mul_f32_e32 v218, v195, v195
	v_pk_add_f32 v[130:131], v[134:135], v[136:137]
	v_pk_add_f32 v[132:133], v[212:213], v[218:219]
	s_nop 0
	v_pk_add_f32 v[130:131], v[130:131], v[132:133]
	s_nop 0
	v_add_f32_e32 v130, v130, v131
	ds_bpermute_b32 v131, v246, v130
	s_waitcnt lgkmcnt(0)
	v_add_f32_e32 v130, v130, v131
	ds_bpermute_b32 v131, v247, v130
	s_waitcnt lgkmcnt(0)
	v_add_f32_e32 v130, v130, v131
	v_fmamk_f32 v130, v130, 0x3c800000, v227
	v_cmp_gt_f32_e32 vcc, s36, v130
	v_mul_f32_e32 v131, 0x4b800000, v130
	s_nop 0
	v_cndmask_b32_e32 v130, v130, v131, vcc
	v_rsq_f32_e32 v130, v130
	s_nop 0
	v_mul_f32_e32 v131, 0x45800000, v130
	v_cndmask_b32_e32 v130, v130, v131, vcc
	v_mul_f32_e32 v212, v245, v130
	v_mad_i64_i32 v[130:131], s[4:5], s0, v159, 0
	v_lshl_add_u64 v[192:193], v[130:131], 1, v[170:171]
	global_load_dwordx4 v[134:137], v[204:205], off
	global_load_dwordx4 v[130:133], v[186:187], off
	v_pk_mul_f32 v[218:219], v[216:217], v[212:213] op_sel_hi:[1,0]
	v_pk_mul_f32 v[220:221], v[214:215], v[212:213] op_sel_hi:[1,0]
	global_load_dwordx4 v[214:217], v[168:169], off
	v_pk_mul_f32 v[206:207], v[206:207], v[212:213] op_sel_hi:[1,0]
	v_pk_mul_f32 v[194:195], v[194:195], v[212:213] op_sel_hi:[1,0]
	v_add_u32_e32 v159, 0xa0, v162
	s_waitcnt vmcnt(0)
	v_pk_mul_f32 v[214:215], v[214:215], v[220:221]
	v_pk_mul_f32 v[216:217], v[216:217], v[218:219]
	v_pk_mul_f32 v[218:219], v[138:139], v[212:213] op_sel_hi:[1,0]
	v_pk_mul_f32 v[220:221], v[140:141], v[212:213] op_sel_hi:[1,0]
	global_load_dwordx4 v[138:141], v[168:169], off offset:64
	s_waitcnt vmcnt(0)
	v_pk_mul_f32 v[140:141], v[140:141], v[220:221]
	v_pk_mul_f32 v[138:139], v[138:139], v[218:219]
	v_pk_mul_f32 v[220:221], v[132:133], v[140:141]
	v_pk_mul_f32 v[218:219], v[130:131], v[138:139]
	v_pk_fma_f32 v[220:221], v[136:137], v[216:217], v[220:221] neg_lo:[0,0,1] neg_hi:[0,0,1]
	v_pk_fma_f32 v[218:219], v[134:135], v[214:215], v[218:219] neg_lo:[0,0,1] neg_hi:[0,0,1]
	v_pk_mul_f32 v[134:135], v[134:135], v[138:139]
	v_pk_mul_f32 v[136:137], v[136:137], v[140:141]
	s_nop 0
	v_pk_fma_f32 v[136:137], v[132:133], v[216:217], v[136:137]
	v_pk_fma_f32 v[132:133], v[130:131], v[214:215], v[134:135]
	v_cvt_pk_bf16_f32 v130, v218, v219
	v_cvt_pk_bf16_f32 v131, v220, v221
	v_cvt_pk_bf16_f32 v132, v132, v133
	v_cvt_pk_bf16_f32 v133, v136, v137
	global_store_dwordx4 v[192:193], v[130:133], off
	global_load_dwordx4 v[130:133], v[188:189], off
	s_nop 0
	global_load_dwordx4 v[134:137], v[190:191], off
	global_load_dwordx4 v[138:141], v[168:169], off offset:128
	v_pk_mul_f32 v[188:189], v[208:209], v[212:213] op_sel_hi:[1,0]
	v_pk_mul_f32 v[190:191], v[210:211], v[212:213] op_sel_hi:[1,0]
	s_waitcnt vmcnt(0)
	v_pk_mul_f32 v[188:189], v[140:141], v[188:189]
	v_pk_mul_f32 v[190:191], v[138:139], v[190:191]
	global_load_dwordx4 v[138:141], v[168:169], off offset:192
	s_waitcnt vmcnt(0)
	v_pk_mul_f32 v[140:141], v[140:141], v[194:195]
	v_pk_mul_f32 v[138:139], v[138:139], v[206:207]
	v_pk_mul_f32 v[206:207], v[136:137], v[140:141]
	v_pk_mul_f32 v[194:195], v[134:135], v[138:139]
	v_pk_fma_f32 v[206:207], v[132:133], v[188:189], v[206:207] neg_lo:[0,0,1] neg_hi:[0,0,1]
	v_pk_fma_f32 v[194:195], v[130:131], v[190:191], v[194:195] neg_lo:[0,0,1] neg_hi:[0,0,1]
	v_pk_mul_f32 v[130:131], v[130:131], v[138:139]
	v_pk_mul_f32 v[132:133], v[132:133], v[140:141]
	s_nop 0
	v_pk_fma_f32 v[136:137], v[136:137], v[188:189], v[132:133]
	v_pk_fma_f32 v[132:133], v[134:135], v[190:191], v[130:131]
	v_cvt_pk_bf16_f32 v130, v194, v195
	v_cvt_pk_bf16_f32 v131, v206, v207
	v_cvt_pk_bf16_f32 v132, v132, v133
	v_cvt_pk_bf16_f32 v133, v136, v137
	global_store_dwordx4 v[192:193], v[130:133], off offset:64
	s_nop 1
	v_fmamk_f32 v130, v145, 0x3a800000, v227
	v_cmp_gt_f32_e32 vcc, s36, v130
	v_mul_f32_e32 v131, 0x4b800000, v130
	s_nop 0
	v_cndmask_b32_e32 v130, v130, v131, vcc
	v_rsq_f32_e32 v130, v130
	s_nop 0
	v_mul_f32_e32 v131, 0x45800000, v130
	v_cndmask_b32_e32 v188, v130, v131, vcc
	global_load_dwordx4 v[130:133], v[166:167], off offset:16
	global_load_dwordx4 v[134:137], v[166:167], off
	s_waitcnt vmcnt(1)
	v_pk_fma_f32 v[140:141], v[74:75], v[188:189], v[132:133] op_sel_hi:[1,0,1]
	s_waitcnt vmcnt(0)
	v_pk_fma_f32 v[210:211], v[76:77], v[188:189], v[134:135] op_sel_hi:[1,0,1]
	v_pk_fma_f32 v[212:213], v[78:79], v[188:189], v[136:137] op_sel_hi:[1,0,1]
	v_pk_mul_f32 v[136:137], v[210:211], v[210:211]
	v_pk_mul_f32 v[134:135], v[212:213], v[212:213]
	s_nop 0
	v_pk_mov_b32 v[138:139], v[136:137], v[134:135] op_sel:[1,0]
	v_mov_b32_e32 v137, v135
	v_pk_add_f32 v[134:135], v[138:139], v[136:137]
	v_pk_fma_f32 v[138:139], v[72:73], v[188:189], v[130:131] op_sel_hi:[1,0,1]
	v_pk_mul_f32 v[130:131], v[140:141], v[140:141]
	v_pk_mul_f32 v[132:133], v[138:139], v[138:139]
	v_pk_add_f32 v[208:209], v[134:135], v[134:135] op_sel_hi:[0,1]
	v_pk_mov_b32 v[134:135], v[132:133], v[130:131] op_sel:[1,0]
	v_mov_b32_e32 v133, v131
	v_pk_add_f32 v[130:131], v[134:135], v[132:133]
	s_nop 0
	v_pk_add_f32 v[214:215], v[130:131], v[130:131] op_sel_hi:[0,1]
	global_load_dwordx4 v[130:133], v[166:167], off offset:528
	global_load_dwordx4 v[134:137], v[166:167], off offset:512
	s_waitcnt vmcnt(1)
; __device__ __forceinline__ unsigned pk_bf16(float lo, float hi) { f32x2 v = {lo, hi}; bf16x2_t b = __builtin_convertvector(v, bf16x2_t); return __builtin_bit_cast(unsigned, b); }
;     __device__ __forceinline__ void operator()(const f32x4 (&acc)[2][2][4][2], const Unit& u, int wr, int wc, int fr, int fq) const {
;     ...
;                     ss += __shfl_xor(ss, 16); ss += __shfl_xor(ss, 32);
;                     const float rinv = rsqrtf(ss * (1.0f / 64.0f) + 1e-6f) * osc;
; #pragma unroll
;                     for (int bj = 0; bj < 2; ++bj) {
;                         const int pos = bj == 0 ? (t >> 6) : (t & 63);
;                         const f32x4 c = *(const f32x4*)(ropec + pos * 16 + 4 * fqo), s = *(const f32x4*)(ropes + pos * 16 + 4 * fqo);
;                         const f32x4 x1 = hv[bj][0] * rinv * *(const f32x4*)(gw + 32 * bj), x2 = hv[bj][1] * rinv * *(const f32x4*)(gw + 32 * bj + 16);
;                         const f32x4 o1 = x1 * c - x2 * s, o2 = x2 * c + x1 * s;
;                         u32x4 w; w.x = pk_bf16(o1[0], o1[1]); w.y = pk_bf16(o1[2], o1[3]); w.z = pk_bf16(o2[0], o2[1]); w.w = pk_bf16(o2[2], o2[3]);
;                         *(u32x4*)(base + (size_t)row * pitch + 32 * bj) = w;
	v_pk_fma_f32 v[190:191], v[10:11], v[188:189], v[132:133] op_sel_hi:[1,0,1]
	s_waitcnt vmcnt(0)
	v_pk_fma_f32 v[206:207], v[12:13], v[188:189], v[134:135] op_sel_hi:[1,0,1]
	v_pk_fma_f32 v[194:195], v[14:15], v[188:189], v[136:137] op_sel_hi:[1,0,1]
	v_mul_f32_e32 v134, v206, v206
	v_pk_fma_f32 v[134:135], v[206:207], v[206:207], v[134:135] op_sel_hi:[1,1,0]
	v_pk_fma_f32 v[192:193], v[8:9], v[188:189], v[130:131] op_sel_hi:[1,0,1]
	v_mul_f32_e32 v134, v194, v194
	v_pk_fma_f32 v[136:137], v[194:195], v[194:195], v[134:135] op_sel_hi:[1,1,0]
	v_mul_f32_e32 v134, v192, v192
	v_mul_f32_e32 v136, v193, v193
	v_mul_f32_e32 v208, v190, v190
	v_mul_f32_e32 v214, v191, v191
	v_pk_add_f32 v[130:131], v[134:135], v[136:137]
	v_pk_add_f32 v[132:133], v[208:209], v[214:215]
	s_nop 0
	v_pk_add_f32 v[130:131], v[130:131], v[132:133]
	s_nop 0
	v_add_f32_e32 v130, v130, v131
	ds_bpermute_b32 v131, v246, v130
	s_waitcnt lgkmcnt(0)
	v_add_f32_e32 v130, v130, v131
	ds_bpermute_b32 v131, v247, v130
	s_waitcnt lgkmcnt(0)
	v_add_f32_e32 v130, v130, v131
	v_fmamk_f32 v130, v130, 0x3c800000, v227
	v_cmp_gt_f32_e32 vcc, s36, v130
	v_mul_f32_e32 v131, 0x4b800000, v130
	s_nop 0
	v_cndmask_b32_e32 v130, v130, v131, vcc
	v_rsq_f32_e32 v130, v130
	s_nop 0
	v_mul_f32_e32 v131, 0x45800000, v130
	v_cndmask_b32_e32 v130, v130, v131, vcc
	v_mul_f32_e32 v208, v245, v130
	v_mad_i64_i32 v[130:131], s[4:5], s0, v159, 0
	v_lshl_add_u64 v[188:189], v[130:131], 1, v[170:171]
	global_load_dwordx4 v[134:137], v[204:205], off
	global_load_dwordx4 v[130:133], v[186:187], off
	v_pk_mul_f32 v[214:215], v[212:213], v[208:209] op_sel_hi:[1,0]
	v_pk_mul_f32 v[216:217], v[210:211], v[208:209] op_sel_hi:[1,0]
	global_load_dwordx4 v[210:213], v[168:169], off
	v_pk_mul_f32 v[194:195], v[194:195], v[208:209] op_sel_hi:[1,0]
	v_pk_mul_f32 v[192:193], v[192:193], v[208:209] op_sel_hi:[1,0]
	v_pk_mul_f32 v[190:191], v[190:191], v[208:209] op_sel_hi:[1,0]
	v_add_u32_e32 v159, 0xb0, v162
	s_waitcnt vmcnt(0)
	v_pk_mul_f32 v[210:211], v[210:211], v[216:217]
	v_pk_mul_f32 v[212:213], v[212:213], v[214:215]
	v_pk_mul_f32 v[214:215], v[138:139], v[208:209] op_sel_hi:[1,0]
	v_pk_mul_f32 v[216:217], v[140:141], v[208:209] op_sel_hi:[1,0]
	global_load_dwordx4 v[138:141], v[168:169], off offset:64
	s_waitcnt vmcnt(0)
	v_pk_mul_f32 v[140:141], v[140:141], v[216:217]
	v_pk_mul_f32 v[138:139], v[138:139], v[214:215]
	v_pk_mul_f32 v[216:217], v[132:133], v[140:141]
	v_pk_mul_f32 v[214:215], v[130:131], v[138:139]
	v_pk_fma_f32 v[216:217], v[136:137], v[212:213], v[216:217] neg_lo:[0,0,1] neg_hi:[0,0,1]
	v_pk_fma_f32 v[214:215], v[134:135], v[210:211], v[214:215] neg_lo:[0,0,1] neg_hi:[0,0,1]
	v_pk_mul_f32 v[134:135], v[134:135], v[138:139]
	v_pk_mul_f32 v[136:137], v[136:137], v[140:141]
	s_nop 0
	v_pk_fma_f32 v[136:137], v[132:133], v[212:213], v[136:137]
	v_pk_fma_f32 v[132:133], v[130:131], v[210:211], v[134:135]
	v_cvt_pk_bf16_f32 v130, v214, v215
	v_cvt_pk_bf16_f32 v131, v216, v217
	v_cvt_pk_bf16_f32 v132, v132, v133
	v_cvt_pk_bf16_f32 v133, v136, v137
	global_store_dwordx4 v[188:189], v[130:133], off
	global_load_dwordx4 v[130:133], v[196:197], off
	s_nop 0
	global_load_dwordx4 v[134:137], v[198:199], off
	global_load_dwordx4 v[138:141], v[168:169], off offset:128
	v_pk_mul_f32 v[196:197], v[206:207], v[208:209] op_sel_hi:[1,0]
	s_waitcnt vmcnt(0)
	v_pk_mul_f32 v[194:195], v[140:141], v[194:195]
	v_pk_mul_f32 v[196:197], v[138:139], v[196:197]
	global_load_dwordx4 v[138:141], v[168:169], off offset:192
	s_waitcnt vmcnt(0)
	v_pk_mul_f32 v[140:141], v[140:141], v[190:191]
	v_pk_mul_f32 v[138:139], v[138:139], v[192:193]
	v_pk_mul_f32 v[192:193], v[136:137], v[140:141]
	v_pk_mul_f32 v[190:191], v[134:135], v[138:139]
	v_pk_fma_f32 v[192:193], v[132:133], v[194:195], v[192:193] neg_lo:[0,0,1] neg_hi:[0,0,1]
	v_pk_fma_f32 v[190:191], v[130:131], v[196:197], v[190:191] neg_lo:[0,0,1] neg_hi:[0,0,1]
	v_pk_mul_f32 v[130:131], v[130:131], v[138:139]
	v_pk_mul_f32 v[132:133], v[132:133], v[140:141]
	s_nop 0
	v_pk_fma_f32 v[136:137], v[136:137], v[194:195], v[132:133]
	v_pk_fma_f32 v[132:133], v[134:135], v[196:197], v[130:131]
	v_cvt_pk_bf16_f32 v130, v190, v191
	v_cvt_pk_bf16_f32 v131, v192, v193
	v_cvt_pk_bf16_f32 v132, v132, v133
	v_cvt_pk_bf16_f32 v133, v136, v137
	global_store_dwordx4 v[188:189], v[130:133], off offset:64
	s_nop 1
	v_fmamk_f32 v130, v147, 0x3a800000, v227
	v_cmp_gt_f32_e32 vcc, s36, v130
	v_mul_f32_e32 v131, 0x4b800000, v130
	s_nop 0
	v_cndmask_b32_e32 v130, v130, v131, vcc
	v_rsq_f32_e32 v130, v130
	s_nop 0
	v_mul_f32_e32 v131, 0x45800000, v130
	v_cndmask_b32_e32 v188, v130, v131, vcc
	global_load_dwordx4 v[130:133], v[166:167], off offset:16
	global_load_dwordx4 v[134:137], v[166:167], off
	s_waitcnt vmcnt(1)
	v_pk_fma_f32 v[140:141], v[66:67], v[188:189], v[132:133] op_sel_hi:[1,0,1]
	s_waitcnt vmcnt(0)
; __device__ __forceinline__ unsigned pk_bf16(float lo, float hi) { f32x2 v = {lo, hi}; bf16x2_t b = __builtin_convertvector(v, bf16x2_t); return __builtin_bit_cast(unsigned, b); }
;     __device__ __forceinline__ void operator()(const f32x4 (&acc)[2][2][4][2], const Unit& u, int wr, int wc, int fr, int fq) const {
;     ...
;                         for (int n = 0; n < 2; ++n) { const f32x4 v = acc[ai][bj][m][n] * rv + *(const f32x4*)(bp + bj * HALF + 4 * n); hv[bj][n] = v; ss += (v[0] * v[0] + v[1] * v[1]) + (v[2] * v[2] + v[3] * v[3]); }
;                     ss += __shfl_xor(ss, 16); ss += __shfl_xor(ss, 32);
;                     const float rinv = rsqrtf(ss * (1.0f / 64.0f) + 1e-6f) * osc;
; #pragma unroll
;                     for (int bj = 0; bj < 2; ++bj) {
;                         const int pos = bj == 0 ? (t >> 6) : (t & 63);
;                         const f32x4 c = *(const f32x4*)(ropec + pos * 16 + 4 * fqo), s = *(const f32x4*)(ropes + pos * 16 + 4 * fqo);
;                         const f32x4 x1 = hv[bj][0] * rinv * *(const f32x4*)(gw + 32 * bj), x2 = hv[bj][1] * rinv * *(const f32x4*)(gw + 32 * bj + 16);
;                         const f32x4 o1 = x1 * c - x2 * s, o2 = x2 * c + x1 * s;
;                         u32x4 w; w.x = pk_bf16(o1[0], o1[1]); w.y = pk_bf16(o1[2], o1[3]); w.z = pk_bf16(o2[0], o2[1]); w.w = pk_bf16(o2[2], o2[3]);
;                         *(u32x4*)(base + (size_t)row * pitch + 32 * bj) = w;
	v_pk_fma_f32 v[196:197], v[68:69], v[188:189], v[134:135] op_sel_hi:[1,0,1]
	v_pk_fma_f32 v[198:199], v[70:71], v[188:189], v[136:137] op_sel_hi:[1,0,1]
	v_pk_mul_f32 v[136:137], v[196:197], v[196:197]
	v_pk_mul_f32 v[134:135], v[198:199], v[198:199]
	s_nop 0
	v_pk_mov_b32 v[138:139], v[136:137], v[134:135] op_sel:[1,0]
	v_mov_b32_e32 v137, v135
	v_pk_add_f32 v[134:135], v[138:139], v[136:137]
	v_pk_fma_f32 v[138:139], v[64:65], v[188:189], v[130:131] op_sel_hi:[1,0,1]
	v_pk_mul_f32 v[130:131], v[140:141], v[140:141]
	v_pk_mul_f32 v[132:133], v[138:139], v[138:139]
	v_pk_add_f32 v[194:195], v[134:135], v[134:135] op_sel_hi:[0,1]
	v_pk_mov_b32 v[134:135], v[132:133], v[130:131] op_sel:[1,0]
	v_mov_b32_e32 v133, v131
	v_pk_add_f32 v[130:131], v[134:135], v[132:133]
	s_nop 0
	v_pk_add_f32 v[206:207], v[130:131], v[130:131] op_sel_hi:[0,1]
	global_load_dwordx4 v[130:133], v[166:167], off offset:528
	global_load_dwordx4 v[134:137], v[166:167], off offset:512
	s_waitcnt vmcnt(1)
	v_pk_fma_f32 v[172:173], v[2:3], v[188:189], v[132:133] op_sel_hi:[1,0,1]
	s_waitcnt vmcnt(0)
	v_pk_fma_f32 v[192:193], v[4:5], v[188:189], v[134:135] op_sel_hi:[1,0,1]
	v_pk_fma_f32 v[190:191], v[6:7], v[188:189], v[136:137] op_sel_hi:[1,0,1]
	v_mul_f32_e32 v134, v192, v192
	v_pk_fma_f32 v[134:135], v[192:193], v[192:193], v[134:135] op_sel_hi:[1,1,0]
	v_pk_fma_f32 v[188:189], v[0:1], v[188:189], v[130:131] op_sel_hi:[1,0,1]
	v_mul_f32_e32 v134, v190, v190
	v_pk_fma_f32 v[136:137], v[190:191], v[190:191], v[134:135] op_sel_hi:[1,1,0]
	v_mul_f32_e32 v134, v188, v188
	v_mul_f32_e32 v136, v189, v189
	v_mul_f32_e32 v194, v172, v172
	v_mul_f32_e32 v206, v173, v173
	v_pk_add_f32 v[130:131], v[134:135], v[136:137]
	v_pk_add_f32 v[132:133], v[194:195], v[206:207]
	s_nop 0
	v_pk_add_f32 v[130:131], v[130:131], v[132:133]
	s_nop 0
	v_add_f32_e32 v130, v130, v131
	ds_bpermute_b32 v131, v246, v130
	s_waitcnt lgkmcnt(0)
	v_add_f32_e32 v130, v130, v131
	ds_bpermute_b32 v131, v247, v130
	s_waitcnt lgkmcnt(0)
	v_add_f32_e32 v130, v130, v131
	v_fmamk_f32 v130, v130, 0x3c800000, v227
	v_cmp_gt_f32_e32 vcc, s36, v130
	v_mul_f32_e32 v131, 0x4b800000, v130
	s_nop 0
	v_cndmask_b32_e32 v130, v130, v131, vcc
	v_rsq_f32_e32 v130, v130
	s_nop 0
	v_mul_f32_e32 v131, 0x45800000, v130
	v_cndmask_b32_e32 v130, v130, v131, vcc
	v_mul_f32_e32 v194, v245, v130
	v_mad_i64_i32 v[130:131], s[0:1], s0, v159, 0
	v_lshl_add_u64 v[170:171], v[130:131], 1, v[170:171]
	global_load_dwordx4 v[134:137], v[204:205], off
	global_load_dwordx4 v[130:133], v[186:187], off
	v_pk_mul_f32 v[204:205], v[198:199], v[194:195] op_sel_hi:[1,0]
	v_pk_mul_f32 v[186:187], v[196:197], v[194:195] op_sel_hi:[1,0]
	global_load_dwordx4 v[196:199], v[168:169], off
	v_pk_mul_f32 v[188:189], v[188:189], v[194:195] op_sel_hi:[1,0]
	v_pk_mul_f32 v[172:173], v[172:173], v[194:195] op_sel_hi:[1,0]
	s_mov_b64 s[0:1], 0
	s_waitcnt vmcnt(0)
	v_pk_mul_f32 v[186:187], v[196:197], v[186:187]
	v_pk_mul_f32 v[196:197], v[198:199], v[204:205]
	v_pk_mul_f32 v[198:199], v[138:139], v[194:195] op_sel_hi:[1,0]
	v_pk_mul_f32 v[204:205], v[140:141], v[194:195] op_sel_hi:[1,0]
	global_load_dwordx4 v[138:141], v[168:169], off offset:64
	s_waitcnt vmcnt(0)
	v_pk_mul_f32 v[140:141], v[140:141], v[204:205]
	v_pk_mul_f32 v[138:139], v[138:139], v[198:199]
	v_pk_mul_f32 v[204:205], v[132:133], v[140:141]
	v_pk_mul_f32 v[198:199], v[130:131], v[138:139]
	v_pk_fma_f32 v[204:205], v[136:137], v[196:197], v[204:205] neg_lo:[0,0,1] neg_hi:[0,0,1]
	v_pk_fma_f32 v[198:199], v[134:135], v[186:187], v[198:199] neg_lo:[0,0,1] neg_hi:[0,0,1]
	v_pk_mul_f32 v[134:135], v[134:135], v[138:139]
	v_pk_mul_f32 v[136:137], v[136:137], v[140:141]
	s_nop 0
	v_pk_fma_f32 v[136:137], v[132:133], v[196:197], v[136:137]
	v_pk_fma_f32 v[132:133], v[130:131], v[186:187], v[134:135]
	v_cvt_pk_bf16_f32 v130, v198, v199
	v_cvt_pk_bf16_f32 v131, v204, v205
	v_cvt_pk_bf16_f32 v132, v132, v133
	v_cvt_pk_bf16_f32 v133, v136, v137
	global_store_dwordx4 v[170:171], v[130:133], off
	global_load_dwordx4 v[130:133], v[200:201], off
	s_nop 0
	global_load_dwordx4 v[134:137], v[202:203], off
	global_load_dwordx4 v[138:141], v[168:169], off offset:128
	v_pk_mul_f32 v[186:187], v[190:191], v[194:195] op_sel_hi:[1,0]
	v_pk_mul_f32 v[190:191], v[192:193], v[194:195] op_sel_hi:[1,0]
	s_waitcnt vmcnt(0)
	v_pk_mul_f32 v[186:187], v[140:141], v[186:187]
	v_pk_mul_f32 v[190:191], v[138:139], v[190:191]
	global_load_dwordx4 v[138:141], v[168:169], off offset:192
	s_waitcnt vmcnt(0)
	v_pk_mul_f32 v[140:141], v[140:141], v[172:173]
	v_pk_mul_f32 v[138:139], v[138:139], v[188:189]
	v_pk_mul_f32 v[172:173], v[136:137], v[140:141]
	v_pk_mul_f32 v[168:169], v[134:135], v[138:139]
	v_pk_fma_f32 v[172:173], v[132:133], v[186:187], v[172:173] neg_lo:[0,0,1] neg_hi:[0,0,1]
	v_pk_fma_f32 v[168:169], v[130:131], v[190:191], v[168:169] neg_lo:[0,0,1] neg_hi:[0,0,1]
	v_pk_mul_f32 v[130:131], v[130:131], v[138:139]
	v_pk_mul_f32 v[132:133], v[132:133], v[140:141]
	s_nop 0
	v_pk_fma_f32 v[136:137], v[136:137], v[186:187], v[132:133]
	v_pk_fma_f32 v[132:133], v[134:135], v[190:191], v[130:131]
	v_cvt_pk_bf16_f32 v130, v168, v169
	v_cvt_pk_bf16_f32 v131, v172, v173
	v_cvt_pk_bf16_f32 v132, v132, v133
	v_cvt_pk_bf16_f32 v133, v136, v137
	global_store_dwordx4 v[170:171], v[130:133], off offset:64

;     __device__ __forceinline__ void operator()(const f32x4 (&acc)[2][2][4][2], const Unit& u, int wr, int wc, int fr, int fq) const {
;     ...
;                 const f32x4 bz0 = *(const f32x4*)(bp + bj * HALF), bz1 = *(const f32x4*)(bp + bj * HALF + 4);
;                 const float qsc = (pn == 0 || pn == 3 || (pn == 4 && bj == 0)) ? 0.125f * 1.4426950408889634f : 1.0f;
;                 const bool isk = (pn == 1) || (pn == 4 && bj == 1);
;                 float kmx = 0.f;
; #pragma unroll
;                 for (int ai = 0; ai < 2; ++ai)
; #pragma unroll
;                     for (int m = 0; m < 4; ++m) {
;                         const int row = row0 + ai * HALF + m * 16;
;                         const float rv = rsqrtf(rowss[row] * (1.0f / 1024.0f) + 1e-6f);
;                         const f32x4 v0 = (acc[ai][bj][m][0] * rv + bz0) * qsc, v1 = (acc[ai][bj][m][1] * rv + bz1) * qsc;
.LBB0_309:
	s_waitcnt lgkmcnt(0)
	global_load_dwordx4 v[64:67], v[166:167], off offset:528
	global_load_dwordx4 v[68:71], v[166:167], off offset:512
	global_load_dword v72, v[138:139], off
	global_load_dword v201, v[138:139], off offset:64
	s_cmp_eq_u32 s66, 3
	s_cselect_b64 s[74:75], -1, 0
	s_cmp_eq_u32 s66, 0
	s_cselect_b64 s[4:5], -1, 0
	s_cmp_lt_i32 s66, 4
	s_waitcnt vmcnt(0)
	v_fmamk_f32 v72, v72, 0x3a800000, v227
	v_cmp_gt_f32_e64 s[0:1], s36, v72
	s_cbranch_scc1 .LBB0_311
	s_cmp_eq_u32 s66, 4
	s_cselect_b64 s[6:7], -1, 0
	s_cbranch_execz .LBB0_312
	s_branch .LBB0_313

; __device__ __forceinline__ unsigned pk_bf16(float lo, float hi) { f32x2 v = {lo, hi}; bf16x2_t b = __builtin_convertvector(v, bf16x2_t); return __builtin_bit_cast(unsigned, b); }
;     __device__ __forceinline__ void operator()(const f32x4 (&acc)[2][2][4][2], const Unit& u, int wr, int wc, int fr, int fq) const {
;     ...
;                         const float rv = rsqrtf(rowss[row] * (1.0f / 1024.0f) + 1e-6f);
;                         const f32x4 v0 = (acc[ai][bj][m][0] * rv + bz0) * qsc, v1 = (acc[ai][bj][m][1] * rv + bz1) * qsc;
;                         if (isk) { float s2 = (v0[0] * v0[0] + v0[1] * v0[1]) + (v0[2] * v0[2] + v0[3] * v0[3]) + (v1[0] * v1[0] + v1[1] * v1[1]) + (v1[2] * v1[2] + v1[3] * v1[3]);
;                             s2 += __shfl_xor(s2, 16); s2 += __shfl_xor(s2, 32); kmx = fmaxf(kmx, s2); }
;                         u32x4 w; w.x = pk_bf16(v0[0], v0[1]); w.y = pk_bf16(v0[2], v0[3]); w.z = pk_bf16(v1[0], v1[1]); w.w = pk_bf16(v1[2], v1[3]);
;                         *(u32x4*)(base + (size_t)row * pitch) = w;
.LBB0_315:
	s_lshl_b64 s[0:1], s[86:87], 1
	s_add_u32 s0, s2, s0
	s_addc_u32 s1, s3, s1
	s_lshl_b32 s4, s54, 1
	s_add_u32 s0, s0, s4
	s_addc_u32 s1, s1, 0
	s_add_u32 s0, s0, s59
	s_addc_u32 s1, s1, 0
	v_lshl_add_u64 v[56:57], v[164:165], 1, s[0:1]
	v_cvt_pk_bf16_f32 v85, v58, v59
	v_mad_i64_i32 v[58:59], s[0:1], s42, v162, 0
	v_cvt_pk_bf16_f32 v82, v62, v63
	v_cvt_pk_bf16_f32 v83, v60, v61
	v_cvt_pk_bf16_f32 v84, v74, v75
	v_lshl_add_u64 v[58:59], v[58:59], 1, v[56:57]
	global_store_dwordx4 v[58:59], v[82:85], off
	s_nop 0
	v_readlane_b32 s86, v252, 36
	v_mov_b32_e32 v73, v72
	s_cmp_lt_i32 s66, 4
	s_mov_b32 s94, s86
	v_readlane_b32 s87, v252, 37
	v_fmamk_f32 v58, v201, 0x3a800000, v227
	v_cmp_gt_f32_e64 s[0:1], s36, v58
	s_cbranch_scc1 .LBB0_317
	s_cmp_eq_u32 s66, 4
	s_cselect_b64 s[4:5], -1, 0
	s_cbranch_execz .LBB0_318
	s_branch .LBB0_319
